# in-proj GEMM: 16x16x32 bf16 MFMAs (same operands, f32 accumulate), B fragments double-buffered, staging writes follow new accumulator layout
# speedup vs baseline: 1.1633x; 1.0127x over previous
; DI int ltid_w(int wave) { int t; asm volatile("v_mbcnt_lo_u32_b32 %0, -1, 0\n\tv_mbcnt_hi_u32_b32 %0, -1, %0" : "=v"(t)); return (wave << 6) | t; }
; template <int WM, class Epi>
; DI void gemm_mfma(const bf16_t* __restrict__ A, const bf16_t* __restrict__ Bt, int Arows, int Brows, int MT, int NT, unsigned char* smem, int bid, int nb, int wave, Epi epi) {
;     ...
;   const int tid = ltid_w(wave), lane = tid & 63, wv = tid >> 6;
;   const int wm = wv >> 1, wn = wv & 1;
;   const int r = lane & 31, h = lane >> 5;
;   const int lrow = lane >> 2, lpc = lane & 3;
;   const unsigned lds0 = (unsigned)(size_t)smem;
;   const int rowA = wm * (WM * 32) + r, rowB = wn * 64 + r;
;   const unsigned offA0 = (unsigned)(rowA * 64 + (((0 + h) ^ ((rowA >> 2) & 3)) << 4)), offA1 = (unsigned)(rowA * 64 + (((2 + h) ^ ((rowA >> 2) & 3)) << 4));
;   const unsigned offB0 = (unsigned)(A_BYTES + rowB * 64 + (((0 + h) ^ ((rowB >> 2) & 3)) << 4)), offB1 = (unsigned)(A_BYTES + rowB * 64 + (((2 + h) ^ ((rowB >> 2) & 3)) << 4));
.LBB0_158:
	s_andn2_b64 vcc, exec, s[0:1]
	s_cbranch_vccnz .LBB0_422
	v_readlane_b32 s0, v253, 61
	v_readlane_b32 s1, v253, 62
	s_andn2_b64 vcc, exec, s[0:1]
	v_mbcnt_lo_u32_b32 v0, -1, 0
	v_mbcnt_hi_u32_b32 v0, -1, v0
	s_cbranch_vccnz .LBB0_390
	s_add_u32 s10, s68, 0x41c6000
	s_addc_u32 s11, s69, 0
	s_add_u32 s12, s68, 0xdb56000
	s_addc_u32 s13, s69, 0
	s_mul_i32 s0, s48, 0x4440
	v_readlane_b32 s72, v253, 23
	v_readlane_b32 s73, v253, 24
	s_add_u32 s14, s72, s0
	s_addc_u32 s15, s73, 0
	s_add_u32 s18, s68, 0x15b6000
	s_addc_u32 s19, s69, 0
	s_add_u32 s22, s68, 0x15b7000
	s_addc_u32 s23, s69, 0
	v_readlane_b32 s48, v254, 17
	s_add_u32 s2, s68, 0x1dc6000
	s_addc_u32 s30, s69, 0
	s_mul_i32 s0, s48, 0x8c0000
	s_add_u32 s31, s68, s0
	v_readlane_b32 s0, v253, 39
	s_waitcnt vmcnt(0)
	v_bfe_u32 v158, v0, 5, 1
	v_lshrrev_b32_e32 v4, 2, v0
	v_or_b32_e32 v1, s0, v0
	v_bfe_u32 v5, v0, 2, 2
	v_ashrrev_i32_e32 v156, 6, v1
	v_lshlrev_b32_e32 v3, 6, v1
	v_bitop3_b32 v4, v158, v4, 3 bitop3:0x78
	v_bitop3_b32 v5, v158, v5, 2 bitop3:0x36
	v_and_b32_e32 v2, 1, v156
	v_and_b32_e32 v157, 31, v0
	v_and_b32_e32 v3, 0xffffe7c0, v3
	v_lshlrev_b32_e32 v4, 4, v4
	v_lshlrev_b32_e32 v5, 4, v5
	v_or_b32_e32 v159, v4, v3
	v_or_b32_e32 v164, v5, v3
	v_lshlrev_b32_e32 v3, 12, v2
	v_lshlrev_b32_e32 v6, 6, v157
	v_or3_b32 v3, v3, v6, s39
	v_or_b32_e32 v165, v3, v4
	v_or_b32_e32 v166, v3, v5
	v_bfe_u32 v3, v0, 4, 2
	v_lshlrev_b32_e32 v167, 6, v2
	s_movk_i32 s0, 0xff80
	v_bitop3_b32 v3, v3, v0, 3 bitop3:0x78
	v_and_or_b32 v168, v1, s0, v167
	v_ashrrev_i32_e32 v1, 1, v1
	v_readlane_b32 s72, v254, 15
	v_and_or_b32 v4, v0, 60, v3
	v_and_b32_e32 v169, 0xffffffc0, v1
	v_lshlrev_b32_e32 v0, 4, v0
	v_lshlrev_b32_e32 v1, 4, v3
	s_movk_i32 s0, 0x3c0
	v_readlane_b32 s73, v254, 16
	s_addc_u32 s34, s69, 0
	v_lshlrev_b32_e32 v152, 4, v4
	v_mov_b32_e32 v153, v161
	v_and_or_b32 v154, v0, s0, v1
	v_mov_b32_e32 v155, v161
	v_readlane_b32 s35, v254, 6
	v_readlane_b32 s74, v253, 25
	v_readlane_b32 s75, v253, 26
	v_readlane_b32 s76, v253, 27
	v_readlane_b32 s77, v253, 28
	v_readlane_b32 s78, v253, 29
	v_readlane_b32 s79, v253, 30
	v_readlane_b32 s80, v253, 31
	v_readlane_b32 s81, v253, 32
	v_readlane_b32 s82, v253, 33
	v_readlane_b32 s83, v253, 34
	v_readlane_b32 s84, v253, 35
	v_readlane_b32 s85, v253, 36
	v_readlane_b32 s86, v253, 37
	v_readlane_b32 s87, v253, 38
	v_readlane_b32 s49, v254, 18
	v_and_b32_e32 v0, 15, v157
	v_lshrrev_b32_e32 v1, 4, v157
	v_lshl_or_b32 v1, v158, 1, v1
	v_lshrrev_b32_e32 v2, 1, v1
	v_xor_b32_e32 v2, v2, v1
	v_and_b32_e32 v2, 1, v2
	v_and_b32_e32 v3, 1, v1
	v_lshl_or_b32 v2, v3, 1, v2
	v_lshrrev_b32_e32 v3, 2, v0
	v_xor_b32_e32 v2, v2, v3
	v_lshlrev_b32_e32 v2, 4, v2
	v_lshl_or_b32 v2, v0, 6, v2
	v_lshrrev_b32_e32 v3, 1, v156
	v_lshl_or_b32 v159, v3, 13, v2
	v_and_b32_e32 v3, 1, v156
	v_lshlrev_b32_e32 v3, 12, v3
	v_or_b32_e32 v3, v3, v2
	v_or_b32_e32 v165, 0x4000, v3
	s_branch .LBB0_163

; #define RAW_BARRIER() do { asm volatile("s_waitcnt lgkmcnt(0)" ::: "memory"); __builtin_amdgcn_s_barrier(); } while (0)
; template <int WM, class Epi>
; DI void gemm_mfma(const bf16_t* __restrict__ A, const bf16_t* __restrict__ Bt, int Arows, int Brows, int MT, int NT, unsigned char* smem, int bid, int nb, int wave, Epi epi) {
;     ...
;   for (int li = l0; li < per; li += lstep) {
;     const int wi = xq * per + li;
;     const int patch = wi / (PM * PN), within = wi % (PM * PN);
;     const int mt = epi.mt_of((patch / NPN) * PM + within / PN), nt = (patch % NPN) * PN + within % PN;
;     f32x16 acc[WM][2];
; #pragma unroll
;     for (int a = 0; a < WM; ++a)
; #pragma unroll
;       for (int b = 0; b < 2; ++b)
; #pragma unroll
;         for (int i = 0; i < 16; ++i) acc[a][b][i] = 0.f;
;     constexpr int NAW = NA / 4;
;     const int wvu = __builtin_amdgcn_readfirstlane(wv);
;     const unsigned voff = (unsigned)((lrow * 32 + ((lpc ^ ((lrow >> 2) & 3)) << 3)) * 2);
;     const char* abase = (const char*)(A + (size_t)(mt * BMROWS + wvu * NAW * 16) * 32);
;     const char* bbase = (const char*)(Bt + (size_t)(nt * 128 + wvu * 2 * 16) * 32);
;     const size_t astep = (size_t)Arows * 64, bstep = (size_t)Brows * 64;
;     auto issue = [&](int kt, int buf) {
; #pragma unroll
;       for (int i = 0; i < NAW; ++i)
;         __builtin_amdgcn_global_load_lds((const unsigned*)(abase + kt * astep + i * 1024 + voff),
;                                          (__attribute__((address_space(3))) unsigned*)(smem + buf * STAGE + (wvu * NAW + i) * 1024), 16, 0, 0);
; #pragma unroll
;       for (int i = 0; i < 2; ++i)
;         __builtin_amdgcn_global_load_lds((const unsigned*)(bbase + kt * bstep + i * 1024 + voff),
;                                          (__attribute__((address_space(3))) unsigned*)(smem + buf * STAGE + A_BYTES + (wvu * 2 + i) * 1024), 16, 0, 0);
;     };
;     RAW_BARRIER();
;     constexpr int NST = (WM == 2) ? 4 : 3;
;     constexpr int NKT = K / 32;
; #pragma unroll
;     for (int s = 0; s < NST - 1; ++s) issue(s, s);
;     bf16x8 fa0[WM], fb0[2], fa1[WM], fb1[2];
; #pragma unroll
;     for (int mi = 0; mi < WM; ++mi) { fa0[mi] = bf16x8{0, 0, 0, 0, 0, 0, 0, 0}; fa1[mi] = fa0[mi]; }
;     fb0[0] = bf16x8{0, 0, 0, 0, 0, 0, 0, 0}; fb0[1] = fb0[0]; fb1[0] = fb0[0]; fb1[1] = fb0[0];
.LBB0_163:
	v_readlane_b32 s0, v254, 0
	s_add_i32 s0, s35, s0
	s_lshr_b32 s1, s0, 2
	s_mul_i32 s1, s1, 0x751
	s_lshr_b32 s1, s1, 16
	s_mul_i32 s4, s1, 0x8c
	s_sub_i32 s0, s0, s4
	s_and_b32 s4, s0, 3
	s_lshr_b32 s0, s0, 2
	s_mov_b32 s29, s0
	s_mov_b32 s8, s0
	v_readfirstlane_b32 s20, v156
	s_lshl_b32 s0, s1, 10
	s_lshl_b32 s28, s4, 8
	s_add_i32 s28, s28, s0
	s_lshl_b32 s0, s20, 6
	s_add_i32 s0, s28, s0
	s_ashr_i32 s1, s0, 31
	s_lshl_b64 s[4:5], s[0:1], 6
	s_add_u32 s6, s2, s4
	s_addc_u32 s7, s30, s5
	s_lshl_b32 s24, s8, 7
	s_lshl_b32 s0, s20, 5
	s_add_i32 s0, s24, s0
	s_ashr_i32 s1, s0, 31
	s_lshl_b64 s[0:1], s[0:1], 6
	s_add_u32 s0, s31, s0
	s_addc_u32 s1, s34, s1
	s_lshl_b32 s9, s20, 12
	v_lshl_add_u64 v[0:1], s[6:7], 0, v[152:153]
	s_mov_b32 m0, s9
	s_mov_b64 s[6:7], 0x400
	s_waitcnt lgkmcnt(0)
	s_barrier
	global_load_lds_dwordx4 v[0:1], off
	v_lshl_add_u64 v[2:3], v[0:1], 0, s[6:7]
	s_or_b32 m0, s9, 0x400
	s_mov_b64 s[26:27], 0x800
	global_load_lds_dwordx4 v[2:3], off
	v_lshl_add_u64 v[2:3], v[0:1], 0, s[26:27]
	s_or_b32 m0, s9, 0x800
	s_mov_b64 s[26:27], 0xc00
	s_lshl_b32 s20, s20, 11
	global_load_lds_dwordx4 v[2:3], off
	v_lshl_add_u64 v[2:3], v[0:1], 0, s[26:27]
	s_or_b32 m0, s9, 0xc00
	v_mov_b32_e32 v128, 0
	global_load_lds_dwordx4 v[2:3], off
	v_lshl_add_u64 v[2:3], s[0:1], 0, v[152:153]
	s_add_i32 m0, s20, 0x4000
	v_lshl_add_u64 v[4:5], v[2:3], 0, s[6:7]
	global_load_lds_dwordx4 v[2:3], off
	s_add_i32 m0, s20, 0x4400
	s_mov_b64 s[6:7], 0x120000
	global_load_lds_dwordx4 v[4:5], off
	v_lshl_add_u64 v[4:5], v[0:1], 0, s[6:7]
	s_add_i32 m0, s9, 0x6000
	s_mov_b64 s[6:7], 0x120400
	global_load_lds_dwordx4 v[4:5], off
	v_lshl_add_u64 v[4:5], v[0:1], 0, s[6:7]
	s_add_i32 m0, s9, 0x6400
	s_mov_b64 s[6:7], 0x120800
	global_load_lds_dwordx4 v[4:5], off
	v_lshl_add_u64 v[4:5], v[0:1], 0, s[6:7]
	s_add_i32 m0, s9, 0x6800
	s_mov_b64 s[6:7], 0x120c00
	global_load_lds_dwordx4 v[4:5], off
	v_lshl_add_u64 v[0:1], v[0:1], 0, s[6:7]
	s_add_i32 m0, s9, 0x6c00
	s_mov_b64 s[6:7], 0x46000
	global_load_lds_dwordx4 v[0:1], off
	v_lshl_add_u64 v[0:1], v[2:3], 0, s[6:7]
	s_add_i32 m0, s20, 0xa000
	s_mov_b64 s[6:7], 0x46400
	global_load_lds_dwordx4 v[0:1], off
	v_lshl_add_u64 v[0:1], v[2:3], 0, s[6:7]
	s_add_i32 m0, s20, 0xa400
	s_add_u32 s4, s68, s4
	global_load_lds_dwordx4 v[0:1], off
	v_mov_b32_e32 v0, 0
	s_addc_u32 s5, s69, s5
	s_mov_b32 s21, 2
	v_mov_b32_e32 v1, v0
	v_mov_b32_e32 v2, v0
	v_mov_b32_e32 v3, v0
	v_mov_b32_e32 v4, v0
	v_mov_b32_e32 v5, v0
	v_mov_b32_e32 v6, v0
	v_mov_b32_e32 v7, v0
	v_mov_b32_e32 v8, v0
	v_mov_b32_e32 v9, v0
	v_mov_b32_e32 v10, v0
	v_mov_b32_e32 v11, v0
	v_mov_b32_e32 v12, v0
	v_mov_b32_e32 v13, v0
	v_mov_b32_e32 v14, v0
	v_mov_b32_e32 v15, v0
	v_mov_b32_e32 v16, v0
	v_mov_b32_e32 v17, v0
	v_mov_b32_e32 v18, v0
	v_mov_b32_e32 v19, v0
	v_mov_b32_e32 v20, v0
	v_mov_b32_e32 v21, v0
	v_mov_b32_e32 v22, v0
	v_mov_b32_e32 v23, v0
	v_mov_b32_e32 v24, v0
	v_mov_b32_e32 v25, v0
	v_mov_b32_e32 v26, v0
	v_mov_b32_e32 v27, v0
	v_mov_b32_e32 v28, v0
	v_mov_b32_e32 v29, v0
	v_mov_b32_e32 v30, v0
	v_mov_b32_e32 v31, v0
	v_mov_b32_e32 v32, v0
	v_mov_b32_e32 v33, v0
	v_mov_b32_e32 v34, v0
	v_mov_b32_e32 v35, v0
	v_mov_b32_e32 v36, v0
	v_mov_b32_e32 v37, v0
	v_mov_b32_e32 v38, v0
	v_mov_b32_e32 v39, v0
	v_mov_b32_e32 v40, v0
	v_mov_b32_e32 v41, v0
	v_mov_b32_e32 v42, v0
	v_mov_b32_e32 v43, v0
	v_mov_b32_e32 v44, v0
	v_mov_b32_e32 v45, v0
	v_mov_b32_e32 v46, v0
	v_mov_b32_e32 v47, v0
	v_mov_b32_e32 v48, v0
	v_mov_b32_e32 v49, v0
	v_mov_b32_e32 v50, v0
	v_mov_b32_e32 v51, v0
	v_mov_b32_e32 v52, v0
	v_mov_b32_e32 v53, v0
	v_mov_b32_e32 v54, v0
	v_mov_b32_e32 v55, v0
	v_mov_b32_e32 v56, v0
	v_mov_b32_e32 v57, v0
	v_mov_b32_e32 v58, v0
	v_mov_b32_e32 v59, v0
	v_mov_b32_e32 v60, v0
	v_mov_b32_e32 v61, v0
	v_mov_b32_e32 v62, v0
	v_mov_b32_e32 v63, v0
	v_mov_b32_e32 v64, v0
	v_mov_b32_e32 v65, v0
	v_mov_b32_e32 v66, v0
	v_mov_b32_e32 v67, v0
	v_mov_b32_e32 v68, v0
	v_mov_b32_e32 v69, v0
	v_mov_b32_e32 v70, v0
	v_mov_b32_e32 v71, v0
	v_mov_b32_e32 v72, v0
	v_mov_b32_e32 v73, v0
	v_mov_b32_e32 v74, v0
	v_mov_b32_e32 v75, v0
	v_mov_b32_e32 v76, v0
	v_mov_b32_e32 v77, v0
	v_mov_b32_e32 v78, v0
	v_mov_b32_e32 v79, v0
	v_mov_b32_e32 v80, v0
	v_mov_b32_e32 v81, v0
	v_mov_b32_e32 v82, v0
	v_mov_b32_e32 v83, v0
	v_mov_b32_e32 v84, v0
	v_mov_b32_e32 v85, v0
	v_mov_b32_e32 v86, v0
	v_mov_b32_e32 v87, v0
	v_mov_b32_e32 v88, v0
	v_mov_b32_e32 v89, v0
	v_mov_b32_e32 v90, v0
	v_mov_b32_e32 v91, v0
	v_mov_b32_e32 v92, v0
	v_mov_b32_e32 v93, v0
	v_mov_b32_e32 v94, v0
	v_mov_b32_e32 v95, v0
	v_mov_b32_e32 v96, v0
	v_mov_b32_e32 v97, v0
	v_mov_b32_e32 v98, v0
	v_mov_b32_e32 v99, v0
	v_mov_b32_e32 v100, v0
	v_mov_b32_e32 v101, v0
	v_mov_b32_e32 v102, v0
	v_mov_b32_e32 v103, v0
	v_mov_b32_e32 v104, v0
	v_mov_b32_e32 v105, v0
	v_mov_b32_e32 v106, v0
	v_mov_b32_e32 v107, v0
	v_mov_b32_e32 v108, v0
	v_mov_b32_e32 v109, v0
	v_mov_b32_e32 v110, v0
	v_mov_b32_e32 v111, v0
	v_mov_b32_e32 v112, v0
	v_mov_b32_e32 v113, v0
	v_mov_b32_e32 v114, v0
	v_mov_b32_e32 v115, v0
	v_mov_b32_e32 v116, v0
	v_mov_b32_e32 v117, v0
	v_mov_b32_e32 v118, v0
	v_mov_b32_e32 v119, v0
	v_mov_b32_e32 v120, v0
	v_mov_b32_e32 v121, v0
	v_mov_b32_e32 v122, v0
	v_mov_b32_e32 v123, v0
	v_mov_b32_e32 v124, v0
	v_mov_b32_e32 v125, v0
	v_mov_b32_e32 v126, v0
	v_mov_b32_e32 v127, v0
	v_mov_b32_e32 v129, v128
	v_mov_b32_e32 v130, v128
	v_mov_b32_e32 v131, v128
	v_mov_b32_e32 v132, v128
	v_mov_b32_e32 v133, v128
	v_mov_b32_e32 v134, v128
	v_mov_b32_e32 v135, v128
	v_mov_b32_e32 v140, v128
	v_mov_b32_e32 v141, v128
	v_mov_b32_e32 v142, v128
	v_mov_b32_e32 v143, v128
	v_mov_b32_e32 v148, v128
	v_mov_b32_e32 v149, v128
	v_mov_b32_e32 v150, v128
	v_mov_b32_e32 v151, v128
	v_mov_b32_e32 v136, v128
	v_mov_b32_e32 v137, v128
	v_mov_b32_e32 v138, v128
	v_mov_b32_e32 v139, v128
	v_mov_b32_e32 v144, v128
	v_mov_b32_e32 v145, v128
	v_mov_b32_e32 v146, v128
	v_mov_b32_e32 v147, v128
	v_mov_b32_e32 v228, v128
	v_mov_b32_e32 v229, v128
	v_mov_b32_e32 v230, v128
	v_mov_b32_e32 v231, v128
	v_mov_b32_e32 v232, v128
	v_mov_b32_e32 v233, v128
	v_mov_b32_e32 v234, v128
	v_mov_b32_e32 v235, v128
	s_branch .LBB0_165
; #define RAW_BARRIER() do { asm volatile("s_waitcnt lgkmcnt(0)" ::: "memory"); __builtin_amdgcn_s_barrier(); } while (0)
; #define GEMM_READ4(A_, B_, FA, FB) asm volatile( \
;         "ds_read_b128 %0, %6\n\tds_read_b128 %1, %6 offset:2048\n\tds_read_b128 %2, %6 offset:4096\n\tds_read_b128 %3, %6 offset:6144\n\t" \
;         "ds_read_b128 %4, %7\n\tds_read_b128 %5, %7 offset:2048" \
;         : "=&v"(FA[0]), "=&v"(FA[1]), "=&v"(FA[2]), "=&v"(FA[3]), "=&v"(FB[0]), "=&v"(FB[1]) : "v"(A_), "v"(B_) : "memory")
; #define GEMM_READ2(A_, B_, FA, FB) asm volatile( \
;         "ds_read_b128 %0, %4\n\tds_read_b128 %1, %4 offset:2048\n\tds_read_b128 %2, %5\n\tds_read_b128 %3, %5 offset:2048" \
;         : "=&v"(FA[0]), "=&v"(FA[1]), "=&v"(FB[0]), "=&v"(FB[1]) : "v"(A_), "v"(B_) : "memory")
; #define GEMM_WAIT4(FA, FB) asm volatile("s_waitcnt lgkmcnt(0)" : "+v"(FA[0]), "+v"(FA[1]), "+v"(FA[2]), "+v"(FA[3]), "+v"(FB[0]), "+v"(FB[1]) :: "memory")
; #define GEMM_WAIT2(FA, FB) asm volatile("s_waitcnt lgkmcnt(0)" : "+v"(FA[0]), "+v"(FA[1]), "+v"(FB[0]), "+v"(FB[1]) :: "memory")
; template <int WM, class Epi>
; DI void gemm_mfma(const bf16_t* __restrict__ A, const bf16_t* __restrict__ Bt, int Arows, int Brows, int MT, int NT, unsigned char* smem, int bid, int nb, int wave, Epi epi) {
;     ...
; #pragma unroll 1
;     for (int kt = 0; kt < NKT; ++kt) {
;       const int ahead = (NKT - 1 - kt < NST - 2) ? (NKT - 1 - kt) : (NST - 2);
;       if (NI == 4) { if (ahead == 2) asm volatile("s_waitcnt vmcnt(8)" ::: "memory"); else if (ahead == 1) asm volatile("s_waitcnt vmcnt(4)" ::: "memory"); else asm volatile("s_waitcnt vmcnt(0)" ::: "memory"); }
;       else { if (ahead == 1) asm volatile("s_waitcnt vmcnt(6)" ::: "memory"); else asm volatile("s_waitcnt vmcnt(0)" ::: "memory"); }
;       RAW_BARRIER();
;       if (kt + NST - 1 < NKT) issue(kt + NST - 1, (kt + NST - 1) % NST);
;       const unsigned sb = lds0 + (unsigned)((kt % NST) * STAGE);
;       const unsigned a0 = sb + offA0, a1 = sb + offA1, b0 = sb + offB0, b1 = sb + offB1;
;       if constexpr (WM == 4) GEMM_READ4(a0, b0, fa0, fb0); else GEMM_READ2(a0, b0, fa0, fb0);
;       GEMM_MMA(fa1, fb1);
;       if constexpr (WM == 4) { GEMM_WAIT4(fa0, fb0); GEMM_READ4(a1, b1, fa1, fb1); } else { GEMM_WAIT2(fa0, fb0); GEMM_READ2(a1, b1, fa1, fb1); }
;       GEMM_MMA(fa0, fb0);
;     }
.LBB0_165:
	s_waitcnt vmcnt(6)
	s_waitcnt lgkmcnt(0)
	s_add_i32 s6, s21, -2
	s_barrier
	s_cmp_gt_u32 s21, 31
	s_cbranch_scc1 .Lg16_tail
	s_setprio 1
	v_mfma_f32_16x16x32_bf16 v[0:3], v[128:131], v[144:147], v[0:3]
	s_mul_i32 s7, s21, 0xab
	s_bfe_u32 s7, s7, 0x70009
	s_mul_i32 s7, s7, 3
	s_sub_i32 s7, s21, s7
	s_and_b32 s7, s7, 0xff
	s_mulk_i32 s7, 0x6000
	s_add_i32 s25, s7, s9
	s_add_i32 s7, s7, s20
	s_mul_i32 s26, s6, 0xab
	s_bfe_u32 s26, s26, 0x70009
	s_mul_i32 s26, s26, 3
	s_sub_i32 s6, s6, s26
	s_and_b32 s6, s6, 0xff
	s_mulk_i32 s6, 0x6000
	v_add_u32_e32 v160, s6, v159
	v_add_u32_e32 v170, s6, v165
	ds_read_b128 v[196:199], v160
	ds_read_b128 v[200:203], v160 offset:1024
	v_mfma_f32_16x16x32_bf16 v[4:7], v[128:131], v[148:151], v[4:7]
	ds_read_b128 v[204:207], v160 offset:2048
	ds_read_b128 v[208:211], v160 offset:3072
	v_mfma_f32_16x16x32_bf16 v[8:11], v[128:131], v[228:231], v[8:11]
	ds_read_b128 v[212:215], v170
	ds_read_b128 v[216:219], v170 offset:1024
	v_mfma_f32_16x16x32_bf16 v[12:15], v[128:131], v[232:235], v[12:15]
	ds_read_b128 v[220:223], v170 offset:2048
	ds_read_b128 v[224:227], v170 offset:3072
	s_add_u32 s98, s0, 0x8c000
	s_addc_u32 s99, s1, 0
	s_add_u32 s100, s4, 0x2006000
	s_addc_u32 s101, s5, 0
	s_add_i32 m0, s7, 0x4000
	v_mfma_f32_16x16x32_bf16 v[16:19], v[132:135], v[144:147], v[16:19]
	global_load_lds_dwordx4 v154, s[98:99]
	v_mfma_f32_16x16x32_bf16 v[20:23], v[132:135], v[148:151], v[20:23]
	v_mfma_f32_16x16x32_bf16 v[24:27], v[132:135], v[228:231], v[24:27]
	global_load_lds_dwordx4 v154, s[98:99] offset:1024
	s_mov_b32 m0, s25
	v_mfma_f32_16x16x32_bf16 v[28:31], v[132:135], v[232:235], v[28:31]
	v_mfma_f32_16x16x32_bf16 v[32:35], v[136:139], v[144:147], v[32:35]
	global_load_lds_dwordx4 v154, s[100:101]
	v_mfma_f32_16x16x32_bf16 v[36:39], v[136:139], v[148:151], v[36:39]
	v_mfma_f32_16x16x32_bf16 v[40:43], v[136:139], v[228:231], v[40:43]
	global_load_lds_dwordx4 v154, s[100:101] offset:1024
	v_mfma_f32_16x16x32_bf16 v[44:47], v[136:139], v[232:235], v[44:47]
	v_mfma_f32_16x16x32_bf16 v[48:51], v[140:143], v[144:147], v[48:51]
	v_mfma_f32_16x16x32_bf16 v[52:55], v[140:143], v[148:151], v[52:55]
	v_mfma_f32_16x16x32_bf16 v[56:59], v[140:143], v[228:231], v[56:59]
	v_mfma_f32_16x16x32_bf16 v[60:63], v[140:143], v[232:235], v[60:63]
	s_setprio 0
	s_waitcnt lgkmcnt(0)
	ds_read_b128 v[128:131], v160 offset:4096
	ds_read_b128 v[132:135], v160 offset:5120
	ds_read_b128 v[136:139], v160 offset:6144
	ds_read_b128 v[140:143], v160 offset:7168
	s_setprio 1
	v_mfma_f32_16x16x32_bf16 v[64:67], v[196:199], v[212:215], v[64:67]
	v_mfma_f32_16x16x32_bf16 v[68:71], v[196:199], v[216:219], v[68:71]
	global_load_lds_dwordx4 v154, s[100:101] offset:2048
	v_mfma_f32_16x16x32_bf16 v[72:75], v[196:199], v[220:223], v[72:75]
	v_mfma_f32_16x16x32_bf16 v[76:79], v[196:199], v[224:227], v[76:79]
	v_mfma_f32_16x16x32_bf16 v[80:83], v[200:203], v[212:215], v[80:83]
	global_load_lds_dwordx4 v154, s[100:101] offset:3072
	v_mfma_f32_16x16x32_bf16 v[84:87], v[200:203], v[216:219], v[84:87]
	v_mfma_f32_16x16x32_bf16 v[88:91], v[200:203], v[220:223], v[88:91]
	v_mfma_f32_16x16x32_bf16 v[92:95], v[200:203], v[224:227], v[92:95]
	v_mfma_f32_16x16x32_bf16 v[96:99], v[204:207], v[212:215], v[96:99]
	v_mfma_f32_16x16x32_bf16 v[100:103], v[204:207], v[216:219], v[100:103]
	v_mfma_f32_16x16x32_bf16 v[104:107], v[204:207], v[220:223], v[104:107]
	v_mfma_f32_16x16x32_bf16 v[108:111], v[204:207], v[224:227], v[108:111]
	v_mfma_f32_16x16x32_bf16 v[112:115], v[208:211], v[212:215], v[112:115]
	v_mfma_f32_16x16x32_bf16 v[116:119], v[208:211], v[216:219], v[116:119]
	v_mfma_f32_16x16x32_bf16 v[120:123], v[208:211], v[220:223], v[120:123]
	v_mfma_f32_16x16x32_bf16 v[124:127], v[208:211], v[224:227], v[124:127]
	s_setprio 0
	s_add_u32 s0, s0, 0x46000
	s_addc_u32 s1, s1, 0
	s_add_u32 s4, s4, 0x120000
	s_addc_u32 s5, s5, 0
	s_add_i32 s21, s21, 1
	s_waitcnt vmcnt(6)
	s_waitcnt lgkmcnt(0)
	s_add_i32 s6, s21, -2
	s_barrier
	s_setprio 1
	v_mfma_f32_16x16x32_bf16 v[0:3], v[128:131], v[212:215], v[0:3]
	s_mul_i32 s7, s21, 0xab
	s_bfe_u32 s7, s7, 0x70009
	s_mul_i32 s7, s7, 3
	s_sub_i32 s7, s21, s7
	s_and_b32 s7, s7, 0xff
	s_mulk_i32 s7, 0x6000
	s_add_i32 s25, s7, s9
	s_add_i32 s7, s7, s20
	s_mul_i32 s26, s6, 0xab
	s_bfe_u32 s26, s26, 0x70009
	s_mul_i32 s26, s26, 3
	s_sub_i32 s6, s6, s26
	s_and_b32 s6, s6, 0xff
	s_mulk_i32 s6, 0x6000
	v_add_u32_e32 v160, s6, v159
	v_add_u32_e32 v170, s6, v165
	ds_read_b128 v[196:199], v160
	ds_read_b128 v[200:203], v160 offset:1024
	v_mfma_f32_16x16x32_bf16 v[4:7], v[128:131], v[216:219], v[4:7]
	ds_read_b128 v[204:207], v160 offset:2048
	ds_read_b128 v[208:211], v160 offset:3072
	v_mfma_f32_16x16x32_bf16 v[8:11], v[128:131], v[220:223], v[8:11]
	ds_read_b128 v[144:147], v170
	ds_read_b128 v[148:151], v170 offset:1024
	v_mfma_f32_16x16x32_bf16 v[12:15], v[128:131], v[224:227], v[12:15]
	ds_read_b128 v[228:231], v170 offset:2048
	ds_read_b128 v[232:235], v170 offset:3072
	s_add_u32 s98, s0, 0x8c000
	s_addc_u32 s99, s1, 0
	s_add_u32 s100, s4, 0x2006000
	s_addc_u32 s101, s5, 0
	s_add_i32 m0, s7, 0x4000
	v_mfma_f32_16x16x32_bf16 v[16:19], v[132:135], v[212:215], v[16:19]
	global_load_lds_dwordx4 v154, s[98:99]
	v_mfma_f32_16x16x32_bf16 v[20:23], v[132:135], v[216:219], v[20:23]
	v_mfma_f32_16x16x32_bf16 v[24:27], v[132:135], v[220:223], v[24:27]
	global_load_lds_dwordx4 v154, s[98:99] offset:1024
	s_mov_b32 m0, s25
	v_mfma_f32_16x16x32_bf16 v[28:31], v[132:135], v[224:227], v[28:31]
	v_mfma_f32_16x16x32_bf16 v[32:35], v[136:139], v[212:215], v[32:35]
	global_load_lds_dwordx4 v154, s[100:101]
	v_mfma_f32_16x16x32_bf16 v[36:39], v[136:139], v[216:219], v[36:39]
	v_mfma_f32_16x16x32_bf16 v[40:43], v[136:139], v[220:223], v[40:43]
	global_load_lds_dwordx4 v154, s[100:101] offset:1024
	v_mfma_f32_16x16x32_bf16 v[44:47], v[136:139], v[224:227], v[44:47]
	v_mfma_f32_16x16x32_bf16 v[48:51], v[140:143], v[212:215], v[48:51]
	v_mfma_f32_16x16x32_bf16 v[52:55], v[140:143], v[216:219], v[52:55]
	v_mfma_f32_16x16x32_bf16 v[56:59], v[140:143], v[220:223], v[56:59]
	v_mfma_f32_16x16x32_bf16 v[60:63], v[140:143], v[224:227], v[60:63]
	s_setprio 0
	s_waitcnt lgkmcnt(0)
; #define RAW_BARRIER() do { asm volatile("s_waitcnt lgkmcnt(0)" ::: "memory"); __builtin_amdgcn_s_barrier(); } while (0)
; #define GEMM_READ4(A_, B_, FA, FB) asm volatile( \
;         "ds_read_b128 %0, %6\n\tds_read_b128 %1, %6 offset:2048\n\tds_read_b128 %2, %6 offset:4096\n\tds_read_b128 %3, %6 offset:6144\n\t" \
;         "ds_read_b128 %4, %7\n\tds_read_b128 %5, %7 offset:2048" \
;         : "=&v"(FA[0]), "=&v"(FA[1]), "=&v"(FA[2]), "=&v"(FA[3]), "=&v"(FB[0]), "=&v"(FB[1]) : "v"(A_), "v"(B_) : "memory")
; #define GEMM_READ2(A_, B_, FA, FB) asm volatile( \
;         "ds_read_b128 %0, %4\n\tds_read_b128 %1, %4 offset:2048\n\tds_read_b128 %2, %5\n\tds_read_b128 %3, %5 offset:2048" \
;         : "=&v"(FA[0]), "=&v"(FA[1]), "=&v"(FB[0]), "=&v"(FB[1]) : "v"(A_), "v"(B_) : "memory")
; #define GEMM_WAIT4(FA, FB) asm volatile("s_waitcnt lgkmcnt(0)" : "+v"(FA[0]), "+v"(FA[1]), "+v"(FA[2]), "+v"(FA[3]), "+v"(FB[0]), "+v"(FB[1]) :: "memory")
; #define GEMM_WAIT2(FA, FB) asm volatile("s_waitcnt lgkmcnt(0)" : "+v"(FA[0]), "+v"(FA[1]), "+v"(FB[0]), "+v"(FB[1]) :: "memory")
; template <int WM, class Epi>
; DI void gemm_mfma(const bf16_t* __restrict__ A, const bf16_t* __restrict__ Bt, int Arows, int Brows, int MT, int NT, unsigned char* smem, int bid, int nb, int wave, Epi epi) {
;     ...
; #pragma unroll 1
;     for (int kt = 0; kt < NKT; ++kt) {
;       const int ahead = (NKT - 1 - kt < NST - 2) ? (NKT - 1 - kt) : (NST - 2);
;       if (NI == 4) { if (ahead == 2) asm volatile("s_waitcnt vmcnt(8)" ::: "memory"); else if (ahead == 1) asm volatile("s_waitcnt vmcnt(4)" ::: "memory"); else asm volatile("s_waitcnt vmcnt(0)" ::: "memory"); }
;       else { if (ahead == 1) asm volatile("s_waitcnt vmcnt(6)" ::: "memory"); else asm volatile("s_waitcnt vmcnt(0)" ::: "memory"); }
;       RAW_BARRIER();
;       if (kt + NST - 1 < NKT) issue(kt + NST - 1, (kt + NST - 1) % NST);
;       const unsigned sb = lds0 + (unsigned)((kt % NST) * STAGE);
;       const unsigned a0 = sb + offA0, a1 = sb + offA1, b0 = sb + offB0, b1 = sb + offB1;
;       if constexpr (WM == 4) GEMM_READ4(a0, b0, fa0, fb0); else GEMM_READ2(a0, b0, fa0, fb0);
;       GEMM_MMA(fa1, fb1);
;       if constexpr (WM == 4) { GEMM_WAIT4(fa0, fb0); GEMM_READ4(a1, b1, fa1, fb1); } else { GEMM_WAIT2(fa0, fb0); GEMM_READ2(a1, b1, fa1, fb1); }
;       GEMM_MMA(fa0, fb0);
;     }
	ds_read_b128 v[128:131], v160 offset:4096
	ds_read_b128 v[132:135], v160 offset:5120
	ds_read_b128 v[136:139], v160 offset:6144
	ds_read_b128 v[140:143], v160 offset:7168
	s_setprio 1
	v_mfma_f32_16x16x32_bf16 v[64:67], v[196:199], v[144:147], v[64:67]
	v_mfma_f32_16x16x32_bf16 v[68:71], v[196:199], v[148:151], v[68:71]
	global_load_lds_dwordx4 v154, s[100:101] offset:2048
	v_mfma_f32_16x16x32_bf16 v[72:75], v[196:199], v[228:231], v[72:75]
	v_mfma_f32_16x16x32_bf16 v[76:79], v[196:199], v[232:235], v[76:79]
	v_mfma_f32_16x16x32_bf16 v[80:83], v[200:203], v[144:147], v[80:83]
	global_load_lds_dwordx4 v154, s[100:101] offset:3072
	v_mfma_f32_16x16x32_bf16 v[84:87], v[200:203], v[148:151], v[84:87]
	v_mfma_f32_16x16x32_bf16 v[88:91], v[200:203], v[228:231], v[88:91]
	v_mfma_f32_16x16x32_bf16 v[92:95], v[200:203], v[232:235], v[92:95]
	v_mfma_f32_16x16x32_bf16 v[96:99], v[204:207], v[144:147], v[96:99]
	v_mfma_f32_16x16x32_bf16 v[100:103], v[204:207], v[148:151], v[100:103]
	v_mfma_f32_16x16x32_bf16 v[104:107], v[204:207], v[228:231], v[104:107]
	v_mfma_f32_16x16x32_bf16 v[108:111], v[204:207], v[232:235], v[108:111]
	v_mfma_f32_16x16x32_bf16 v[112:115], v[208:211], v[144:147], v[112:115]
	v_mfma_f32_16x16x32_bf16 v[116:119], v[208:211], v[148:151], v[116:119]
	v_mfma_f32_16x16x32_bf16 v[120:123], v[208:211], v[228:231], v[120:123]
	v_mfma_f32_16x16x32_bf16 v[124:127], v[208:211], v[232:235], v[124:127]
	s_setprio 0
	s_add_u32 s0, s0, 0x46000
	s_addc_u32 s1, s1, 0
	s_add_u32 s4, s4, 0x120000
	s_addc_u32 s5, s5, 0
	s_add_i32 s21, s21, 1
	s_branch .LBB0_165
.Lg16_tail:
	s_setprio 1
	v_mfma_f32_16x16x32_bf16 v[0:3], v[128:131], v[144:147], v[0:3]
	s_mul_i32 s26, s6, 0xab
	s_bfe_u32 s26, s26, 0x70009
	s_mul_i32 s26, s26, 3
	s_sub_i32 s6, s6, s26
	s_and_b32 s6, s6, 0xff
	s_mulk_i32 s6, 0x6000
	v_add_u32_e32 v160, s6, v159
	v_add_u32_e32 v170, s6, v165
	ds_read_b128 v[196:199], v160
	ds_read_b128 v[200:203], v160 offset:1024
	v_mfma_f32_16x16x32_bf16 v[4:7], v[128:131], v[148:151], v[4:7]
	ds_read_b128 v[204:207], v160 offset:2048
	ds_read_b128 v[208:211], v160 offset:3072
	v_mfma_f32_16x16x32_bf16 v[8:11], v[128:131], v[228:231], v[8:11]
	ds_read_b128 v[212:215], v170
	ds_read_b128 v[216:219], v170 offset:1024
	v_mfma_f32_16x16x32_bf16 v[12:15], v[128:131], v[232:235], v[12:15]
	ds_read_b128 v[220:223], v170 offset:2048
	ds_read_b128 v[224:227], v170 offset:3072
	v_mfma_f32_16x16x32_bf16 v[16:19], v[132:135], v[144:147], v[16:19]
	v_mfma_f32_16x16x32_bf16 v[20:23], v[132:135], v[148:151], v[20:23]
	v_mfma_f32_16x16x32_bf16 v[24:27], v[132:135], v[228:231], v[24:27]
	v_mfma_f32_16x16x32_bf16 v[28:31], v[132:135], v[232:235], v[28:31]
	v_mfma_f32_16x16x32_bf16 v[32:35], v[136:139], v[144:147], v[32:35]
	v_mfma_f32_16x16x32_bf16 v[36:39], v[136:139], v[148:151], v[36:39]
	v_mfma_f32_16x16x32_bf16 v[40:43], v[136:139], v[228:231], v[40:43]
	v_mfma_f32_16x16x32_bf16 v[44:47], v[136:139], v[232:235], v[44:47]
	v_mfma_f32_16x16x32_bf16 v[48:51], v[140:143], v[144:147], v[48:51]
	v_mfma_f32_16x16x32_bf16 v[52:55], v[140:143], v[148:151], v[52:55]
	v_mfma_f32_16x16x32_bf16 v[56:59], v[140:143], v[228:231], v[56:59]
	v_mfma_f32_16x16x32_bf16 v[60:63], v[140:143], v[232:235], v[60:63]
	s_setprio 0
	s_waitcnt lgkmcnt(0)
	ds_read_b128 v[128:131], v160 offset:4096
	ds_read_b128 v[132:135], v160 offset:5120
	ds_read_b128 v[136:139], v160 offset:6144
	ds_read_b128 v[140:143], v160 offset:7168
	s_setprio 1
	v_mfma_f32_16x16x32_bf16 v[64:67], v[196:199], v[212:215], v[64:67]
	v_mfma_f32_16x16x32_bf16 v[68:71], v[196:199], v[216:219], v[68:71]
	v_mfma_f32_16x16x32_bf16 v[72:75], v[196:199], v[220:223], v[72:75]
	v_mfma_f32_16x16x32_bf16 v[76:79], v[196:199], v[224:227], v[76:79]
	v_mfma_f32_16x16x32_bf16 v[80:83], v[200:203], v[212:215], v[80:83]
	v_mfma_f32_16x16x32_bf16 v[84:87], v[200:203], v[216:219], v[84:87]
	v_mfma_f32_16x16x32_bf16 v[88:91], v[200:203], v[220:223], v[88:91]
	v_mfma_f32_16x16x32_bf16 v[92:95], v[200:203], v[224:227], v[92:95]
	v_mfma_f32_16x16x32_bf16 v[96:99], v[204:207], v[212:215], v[96:99]
	v_mfma_f32_16x16x32_bf16 v[100:103], v[204:207], v[216:219], v[100:103]
	v_mfma_f32_16x16x32_bf16 v[104:107], v[204:207], v[220:223], v[104:107]
	v_mfma_f32_16x16x32_bf16 v[108:111], v[204:207], v[224:227], v[108:111]
	v_mfma_f32_16x16x32_bf16 v[112:115], v[208:211], v[212:215], v[112:115]
	v_mfma_f32_16x16x32_bf16 v[116:119], v[208:211], v[216:219], v[116:119]
	v_mfma_f32_16x16x32_bf16 v[120:123], v[208:211], v[220:223], v[120:123]
	v_mfma_f32_16x16x32_bf16 v[124:127], v[208:211], v[224:227], v[124:127]
	s_setprio 0
	s_add_u32 s0, s0, 0x46000
	s_addc_u32 s1, s1, 0
	s_add_u32 s4, s4, 0x120000
	s_addc_u32 s5, s5, 0
	s_add_i32 s21, s21, 1
	s_waitcnt vmcnt(0)
	s_waitcnt lgkmcnt(0)
	s_add_i32 s6, s21, -2
	s_barrier
; template <int WM, class Epi>
; DI void gemm_mfma(const bf16_t* __restrict__ A, const bf16_t* __restrict__ Bt, int Arows, int Brows, int MT, int NT, unsigned char* smem, int bid, int nb, int wave, Epi epi) {
;     ...
;     for (int kt = 0; kt < NKT; ++kt) {
;       const int ahead = (NKT - 1 - kt < NST - 2) ? (NKT - 1 - kt) : (NST - 2);
;       if (NI == 4) { if (ahead == 2) asm volatile("s_waitcnt vmcnt(8)" ::: "memory"); else if (ahead == 1) asm volatile("s_waitcnt vmcnt(4)" ::: "memory"); else asm volatile("s_waitcnt vmcnt(0)" ::: "memory"); }
;       else { if (ahead == 1) asm volatile("s_waitcnt vmcnt(6)" ::: "memory"); else asm volatile("s_waitcnt vmcnt(0)" ::: "memory"); }
;       RAW_BARRIER();
;       if (kt + NST - 1 < NKT) issue(kt + NST - 1, (kt + NST - 1) % NST);
;       const unsigned sb = lds0 + (unsigned)((kt % NST) * STAGE);
;       const unsigned a0 = sb + offA0, a1 = sb + offA1, b0 = sb + offB0, b1 = sb + offB1;
;       if constexpr (WM == 4) GEMM_READ4(a0, b0, fa0, fb0); else GEMM_READ2(a0, b0, fa0, fb0);
;       GEMM_MMA(fa1, fb1);
;       if constexpr (WM == 4) { GEMM_WAIT4(fa0, fb0); GEMM_READ4(a1, b1, fa1, fb1); } else { GEMM_WAIT2(fa0, fb0); GEMM_READ2(a1, b1, fa1, fb1); }
;       GEMM_MMA(fa0, fb0);
;     }
;     if constexpr (WM == 4) GEMM_WAIT4(fa1, fb1); else GEMM_WAIT2(fa1, fb1);
;     GEMM_MMA(fa1, fb1);
;   DI void operator()(int mt, int nt, int wm, int wn, int r, int h, f32x16 (&acc)[WM][2]) const {
;     ...
;     const int tid = wm * 128 + wn * 64 + h * 32 + r;
; #pragma unroll
;     for (int ps = 0; ps < WM / 2; ++ps) {
;       RAW_BARRIER();
; #pragma unroll
;       for (int mh = 0; mh < 2; ++mh)
; #pragma unroll
;         for (int ni = 0; ni < 2; ++ni)
; #pragma unroll
;           for (int i = 0; i < 16; ++i)
;             T[(wm * 64 + mh * 32 + (i & 3) + 8 * (i >> 2) + 4 * h) * LD + wn * 64 + ni * 32 + r] = acc[ps * 2 + mh][ni][i];
;       RAW_BARRIER();
;       const int ropemode0 = (nt < 4) ? 1 : ((nt >= 14 && nt <= 16) ? 2 : 0);
; #pragma unroll
;       for (int j = 0; j < 8; ++j) {
;         const int id = tid + 256 * j;
;         const int lr = id >> 4, cc = id & 15;
;         const int row = mt * (WM * 64) + (lr >> 6) * (WM * 32) + ps * 64 + (lr & 63);
;         const int col0 = nt * 128 + cc * 8;
;         if (col0 < PW) {
;           const int t = row % NTOK;
;           const int ropemode = (t >= NCTX) ? ropemode0 : 0;
	s_setprio 1
	v_mfma_f32_16x16x32_bf16 v[0:3], v[128:131], v[212:215], v[0:3]
	s_mul_i32 s26, s6, 0xab
	s_bfe_u32 s26, s26, 0x70009
	s_mul_i32 s26, s26, 3
	s_sub_i32 s6, s6, s26
	s_and_b32 s6, s6, 0xff
	s_mulk_i32 s6, 0x6000
	v_add_u32_e32 v160, s6, v159
	v_add_u32_e32 v170, s6, v165
	ds_read_b128 v[196:199], v160
	ds_read_b128 v[200:203], v160 offset:1024
	v_mfma_f32_16x16x32_bf16 v[4:7], v[128:131], v[216:219], v[4:7]
	ds_read_b128 v[204:207], v160 offset:2048
	ds_read_b128 v[208:211], v160 offset:3072
	v_mfma_f32_16x16x32_bf16 v[8:11], v[128:131], v[220:223], v[8:11]
	ds_read_b128 v[144:147], v170
	ds_read_b128 v[148:151], v170 offset:1024
	v_mfma_f32_16x16x32_bf16 v[12:15], v[128:131], v[224:227], v[12:15]
	ds_read_b128 v[228:231], v170 offset:2048
	ds_read_b128 v[232:235], v170 offset:3072
	v_mfma_f32_16x16x32_bf16 v[16:19], v[132:135], v[212:215], v[16:19]
	v_mfma_f32_16x16x32_bf16 v[20:23], v[132:135], v[216:219], v[20:23]
	v_mfma_f32_16x16x32_bf16 v[24:27], v[132:135], v[220:223], v[24:27]
	v_mfma_f32_16x16x32_bf16 v[28:31], v[132:135], v[224:227], v[28:31]
	v_mfma_f32_16x16x32_bf16 v[32:35], v[136:139], v[212:215], v[32:35]
	v_mfma_f32_16x16x32_bf16 v[36:39], v[136:139], v[216:219], v[36:39]
	v_mfma_f32_16x16x32_bf16 v[40:43], v[136:139], v[220:223], v[40:43]
	v_mfma_f32_16x16x32_bf16 v[44:47], v[136:139], v[224:227], v[44:47]
	v_mfma_f32_16x16x32_bf16 v[48:51], v[140:143], v[212:215], v[48:51]
	v_mfma_f32_16x16x32_bf16 v[52:55], v[140:143], v[216:219], v[52:55]
	v_mfma_f32_16x16x32_bf16 v[56:59], v[140:143], v[220:223], v[56:59]
	v_mfma_f32_16x16x32_bf16 v[60:63], v[140:143], v[224:227], v[60:63]
	s_setprio 0
	s_waitcnt lgkmcnt(0)
	ds_read_b128 v[128:131], v160 offset:4096
	ds_read_b128 v[132:135], v160 offset:5120
	ds_read_b128 v[136:139], v160 offset:6144
	ds_read_b128 v[140:143], v160 offset:7168
	s_setprio 1
	v_mfma_f32_16x16x32_bf16 v[64:67], v[196:199], v[144:147], v[64:67]
	v_mfma_f32_16x16x32_bf16 v[68:71], v[196:199], v[148:151], v[68:71]
	v_mfma_f32_16x16x32_bf16 v[72:75], v[196:199], v[228:231], v[72:75]
	v_mfma_f32_16x16x32_bf16 v[76:79], v[196:199], v[232:235], v[76:79]
	v_mfma_f32_16x16x32_bf16 v[80:83], v[200:203], v[144:147], v[80:83]
	v_mfma_f32_16x16x32_bf16 v[84:87], v[200:203], v[148:151], v[84:87]
	v_mfma_f32_16x16x32_bf16 v[88:91], v[200:203], v[228:231], v[88:91]
	v_mfma_f32_16x16x32_bf16 v[92:95], v[200:203], v[232:235], v[92:95]
	v_mfma_f32_16x16x32_bf16 v[96:99], v[204:207], v[144:147], v[96:99]
	v_mfma_f32_16x16x32_bf16 v[100:103], v[204:207], v[148:151], v[100:103]
	v_mfma_f32_16x16x32_bf16 v[104:107], v[204:207], v[228:231], v[104:107]
	v_mfma_f32_16x16x32_bf16 v[108:111], v[204:207], v[232:235], v[108:111]
	v_mfma_f32_16x16x32_bf16 v[112:115], v[208:211], v[144:147], v[112:115]
	v_mfma_f32_16x16x32_bf16 v[116:119], v[208:211], v[148:151], v[116:119]
	v_mfma_f32_16x16x32_bf16 v[120:123], v[208:211], v[228:231], v[120:123]
	v_mfma_f32_16x16x32_bf16 v[124:127], v[208:211], v[232:235], v[124:127]
	s_setprio 0
	s_add_u32 s0, s0, 0x46000
	s_addc_u32 s1, s1, 0
	s_add_u32 s4, s4, 0x120000
	s_addc_u32 s5, s5, 0
	s_add_i32 s21, s21, 1
	s_waitcnt lgkmcnt(0)
	s_setprio 1
	v_mfma_f32_16x16x32_bf16 v[0:3], v[128:131], v[144:147], v[0:3]
	v_mfma_f32_16x16x32_bf16 v[4:7], v[128:131], v[148:151], v[4:7]
	v_mfma_f32_16x16x32_bf16 v[8:11], v[128:131], v[228:231], v[8:11]
	v_mfma_f32_16x16x32_bf16 v[12:15], v[128:131], v[232:235], v[12:15]
	v_mfma_f32_16x16x32_bf16 v[16:19], v[132:135], v[144:147], v[16:19]
	v_mfma_f32_16x16x32_bf16 v[20:23], v[132:135], v[148:151], v[20:23]
	v_mfma_f32_16x16x32_bf16 v[24:27], v[132:135], v[228:231], v[24:27]
	v_mfma_f32_16x16x32_bf16 v[28:31], v[132:135], v[232:235], v[28:31]
	v_mfma_f32_16x16x32_bf16 v[32:35], v[136:139], v[144:147], v[32:35]
	v_mfma_f32_16x16x32_bf16 v[36:39], v[136:139], v[148:151], v[36:39]
	v_mfma_f32_16x16x32_bf16 v[40:43], v[136:139], v[228:231], v[40:43]
	v_mfma_f32_16x16x32_bf16 v[44:47], v[136:139], v[232:235], v[44:47]
	v_mfma_f32_16x16x32_bf16 v[48:51], v[140:143], v[144:147], v[48:51]
	v_mfma_f32_16x16x32_bf16 v[52:55], v[140:143], v[148:151], v[52:55]
	v_mfma_f32_16x16x32_bf16 v[56:59], v[140:143], v[228:231], v[56:59]
	v_mfma_f32_16x16x32_bf16 v[60:63], v[140:143], v[232:235], v[60:63]
	s_setprio 0
	s_sext_i32_i16 s4, s29
	s_cmp_lt_i32 s4, 4
	s_cselect_b64 s[44:45], -1, 0
	s_sub_i32 s0, s8, 17
	s_cmp_lt_u32 s0, -3
	s_cselect_b64 s[0:1], -1, 0
	s_cmp_gt_i32 s4, 3
	s_cselect_b64 s[4:5], -1, 0
	s_and_b64 s[8:9], s[4:5], exec
	v_mov_b32_e32 v133, v157
	v_mov_b32_e32 v128, v158
	s_cselect_b32 s8, 2, 1
	v_cndmask_b32_e64 v137, 0, 1, s[4:5]
	v_bitop3_b32 v131, v133, s8, 15 bitop3:0x6c
	v_lshlrev_b32_e32 v132, 3, v131
	v_lshrrev_b32_e32 v131, v137, v133
	v_lshlrev_b32_e32 v129, 5, v128
	v_and_b32_e32 v131, 2, v131
	v_add3_u32 v204, v168, v133, v129
	v_lshl_add_u32 v134, v128, 2, v169
	v_add_u32_e32 v135, v133, v167
	v_and_b32_e32 v136, 15, v133
	s_and_b64 s[46:47], s[4:5], s[0:1]
	v_cmp_eq_u32_e64 s[4:5], 0, v131
	v_lshlrev_b32_e32 v131, 3, v133
	v_bfe_u32 v133, v133, v137, 1
	v_cmp_eq_u32_e64 s[0:1], 0, v133
	v_mul_lo_u32 v133, v134, s66
	v_lshl_add_u32 v133, v135, 2, v133
	s_waitcnt lgkmcnt(0)
	s_barrier
; #define RAW_BARRIER() do { asm volatile("s_waitcnt lgkmcnt(0)" ::: "memory"); __builtin_amdgcn_s_barrier(); } while (0)
;   DI void operator()(int mt, int nt, int wm, int wn, int r, int h, f32x16 (&acc)[WM][2]) const {
;     ...
;       RAW_BARRIER();
; #pragma unroll
;       for (int mh = 0; mh < 2; ++mh)
; #pragma unroll
;         for (int ni = 0; ni < 2; ++ni)
; #pragma unroll
;           for (int i = 0; i < 16; ++i)
;             T[(wm * 64 + mh * 32 + (i & 3) + 8 * (i >> 2) + 4 * h) * LD + wn * 64 + ni * 32 + r] = acc[ps * 2 + mh][ni][i];
;       RAW_BARRIER();
;       const int ropemode0 = (nt < 4) ? 1 : ((nt >= 14 && nt <= 16) ? 2 : 0);
; #pragma unroll
;       for (int j = 0; j < 8; ++j) {
;         const int id = tid + 256 * j;
;         const int lr = id >> 4, cc = id & 15;
;         const int row = mt * (WM * 64) + (lr >> 6) * (WM * 32) + ps * 64 + (lr & 63);
;         const int col0 = nt * 128 + cc * 8;
;         if (col0 < PW) {
;           const int t = row % NTOK;
;           const int ropemode = (t >= NCTX) ? ropemode0 : 0;
;           const float4 a0 = *(const float4*)(T + lr * LD + cc * 8), a1 = *(const float4*)(T + lr * LD + cc * 8 + 4);
;           const float4 b0 = *(const float4*)(bias + col0), b1 = *(const float4*)(bias + col0 + 4);
;           float v[8] = {a0.x + b0.x, a0.y + b0.y, a0.z + b0.z, a0.w + b0.w, a1.x + b1.x, a1.y + b1.y, a1.z + b1.z, a1.w + b1.w};
	s_waitcnt vmcnt(0)
	v_lshrrev_b32_e32 v196, 4, v157
	v_lshl_or_b32 v196, v158, 1, v196
	v_lshrrev_b32_e32 v197, 1, v156
	v_lshlrev_b32_e32 v197, 6, v197
	v_lshl_add_u32 v196, v196, 2, v197
	v_mul_u32_u24_e32 v196, 0x210, v196
	v_and_b32_e32 v197, 1, v156
	v_lshl_add_u32 v196, v197, 8, v196
	v_and_b32_e32 v197, 15, v157
	v_lshl_add_u32 v133, v197, 2, v196
	ds_write_b32 v133, v64
	ds_write_b32 v133, v68 offset:64
	ds_write_b32 v133, v72 offset:128
	ds_write_b32 v133, v76 offset:192
	ds_write_b32 v133, v65 offset:528
	ds_write_b32 v133, v69 offset:592
	ds_write_b32 v133, v73 offset:656
	ds_write_b32 v133, v77 offset:720
	ds_write_b32 v133, v66 offset:1056
	ds_write_b32 v133, v70 offset:1120
	ds_write_b32 v133, v74 offset:1184
	ds_write_b32 v133, v78 offset:1248
	ds_write_b32 v133, v67 offset:1584
	ds_write_b32 v133, v71 offset:1648
	ds_write_b32 v133, v75 offset:1712
	ds_write_b32 v133, v79 offset:1776
	ds_write_b32 v133, v80 offset:8448
	ds_write_b32 v133, v84 offset:8512
	ds_write_b32 v133, v88 offset:8576
	ds_write_b32 v133, v92 offset:8640
	ds_write_b32 v133, v81 offset:8976
	ds_write_b32 v133, v85 offset:9040
	ds_write_b32 v133, v89 offset:9104
	ds_write_b32 v133, v93 offset:9168
	ds_write_b32 v133, v82 offset:9504
	ds_write_b32 v133, v86 offset:9568
	ds_write_b32 v133, v90 offset:9632
	ds_write_b32 v133, v94 offset:9696
	ds_write_b32 v133, v83 offset:10032
	ds_write_b32 v133, v87 offset:10096
	ds_write_b32 v133, v91 offset:10160
	ds_write_b32 v133, v95 offset:10224
	ds_write_b32 v133, v96 offset:16896
	ds_write_b32 v133, v100 offset:16960
	ds_write_b32 v133, v104 offset:17024
	ds_write_b32 v133, v108 offset:17088
	ds_write_b32 v133, v97 offset:17424
	ds_write_b32 v133, v101 offset:17488
	ds_write_b32 v133, v105 offset:17552
	ds_write_b32 v133, v109 offset:17616
	ds_write_b32 v133, v98 offset:17952
	ds_write_b32 v133, v102 offset:18016
	ds_write_b32 v133, v106 offset:18080
	ds_write_b32 v133, v110 offset:18144
	ds_write_b32 v133, v99 offset:18480
	ds_write_b32 v133, v103 offset:18544
	ds_write_b32 v133, v107 offset:18608
	ds_write_b32 v133, v111 offset:18672
	ds_write_b32 v133, v112 offset:25344
	ds_write_b32 v133, v116 offset:25408
	ds_write_b32 v133, v120 offset:25472
	ds_write_b32 v133, v124 offset:25536
	ds_write_b32 v133, v113 offset:25872
	ds_write_b32 v133, v117 offset:25936
	ds_write_b32 v133, v121 offset:26000
	ds_write_b32 v133, v125 offset:26064
	ds_write_b32 v133, v114 offset:26400
	ds_write_b32 v133, v118 offset:26464
	ds_write_b32 v133, v122 offset:26528
	ds_write_b32 v133, v126 offset:26592
	ds_write_b32 v133, v115 offset:26928
	ds_write_b32 v133, v119 offset:26992
	ds_write_b32 v133, v123 offset:27056
	ds_write_b32 v133, v127 offset:27120
	v_add_u32_e32 v112, 0x400, v133
	v_add_u32_e32 v113, 0x1000, v133
	v_add_u32_e32 v114, 0x1400, v133
	v_add_u32_e32 v115, 0x2000, v133
	v_add_u32_e32 v116, 0x2400, v133
	v_add_u32_e32 v117, 0x3000, v133
	v_add_u32_e32 v119, 0x3400, v133
	v_add_u32_e32 v120, 0x3600, v133
	v_lshlrev_b32_e32 v130, 3, v136
	v_cmp_gt_u32_e32 vcc, 2, v136
	v_add_u32_e32 v118, 0x3200, v133
	v_add_u32_e32 v121, 0x4000, v133
	v_add_u32_e32 v122, 0x4400, v133
	v_add_u32_e32 v124, 0x4800, v133
	v_add_u32_e32 v126, 0x5000, v133
	v_add_u32_e32 v127, 0x5400, v133
	v_add_u32_e32 v134, 0x5800, v133
	v_add_u32_e32 v135, 0x6000, v133
	v_add_u32_e32 v136, 0x6400, v133
	v_add_u32_e32 v137, 0x6800, v133
	v_add_u32_e32 v139, 0x7200, v133
	v_add_u32_e32 v141, 0x7400, v133
	v_add_u32_e32 v142, 0x7600, v133
	v_add_u32_e32 v143, 0x7800, v133
	s_ashr_i32 s25, s24, 31
	s_and_b32 s43, 0xffff, s29
	v_or_b32_e32 v128, s24, v130
	s_cmp_eq_u32 s43, 24
	s_waitcnt lgkmcnt(0)
	v_ashrrev_i32_e32 v94, 4, v204
	v_ashrrev_i32_e32 v64, 3, v204
	v_ashrrev_i32_e32 v129, 31, v128
	s_cselect_b64 s[8:9], -1, 0
	v_and_b32_e32 v144, 0xffffff80, v64
	v_mul_lo_u32 v102, v94, s66
	v_cmp_gt_i32_e64 s[6:7], s63, v128
	v_and_b32_e32 v131, 8, v131
	s_and_b64 s[40:41], s[8:9], vcc
	v_add_u32_e32 v205, s28, v144
	v_and_b32_e32 v110, 63, v94
	v_lshl_add_u32 v111, v130, 2, v102
	v_lshl_add_u64 v[88:89], v[128:129], 2, s[14:15]
	s_barrier
	s_and_saveexec_b64 s[8:9], s[6:7]
	s_cbranch_execz .LBB0_180
	global_load_dwordx4 v[220:223], v[88:89], off
	global_load_dwordx4 v[224:227], v[88:89], off offset:16
	v_or_b32_e32 v90, v205, v110
	v_mul_hi_i32 v80, v90, s55
	ds_read_b128 v[68:71], v111
	ds_read_b128 v[76:79], v111 offset:16
	v_lshrrev_b32_e32 v81, 31, v80
	v_ashrrev_i32_e32 v80, 9, v80
	v_add_u32_e32 v80, v80, v81
	v_mul_i32_i24_e32 v80, 0x900, v80
	v_sub_u32_e32 v91, v90, v80
	s_xor_b64 s[20:21], s[46:47], -1
	v_cmp_lt_i32_e32 vcc, s62, v91
	s_and_b64 s[26:27], vcc, s[20:21]
	s_waitcnt vmcnt(0) lgkmcnt(0)
	v_pk_add_f32 v[68:69], v[68:69], v[220:221]
	v_pk_add_f32 v[70:71], v[70:71], v[222:223]
	v_pk_add_f32 v[64:65], v[76:77], v[224:225]
	v_pk_add_f32 v[66:67], v[78:79], v[226:227]
	s_and_saveexec_b64 s[20:21], s[26:27]
	s_cbranch_execz .LBB0_178
	s_lshl_b64 s[26:27], s[24:25], 2
	s_add_u32 s26, s14, s26
	v_lshlrev_b32_e32 v76, 2, v132
	s_addc_u32 s27, s15, s27
	global_load_dwordx4 v[72:75], v76, s[26:27] offset:16
	global_load_dwordx4 v[80:83], v76, s[26:27]
	v_add_u32_e32 v76, v102, v76
	ds_read_b128 v[84:87], v76
	ds_read_b128 v[76:79], v76 offset:16
	v_add_u32_e32 v92, 0xffffff00, v91
	v_lshrrev_b32_e32 v92, 6, v92
	v_and_b32_e32 v91, 63, v91
	v_cndmask_b32_e64 v91, v91, v92, s[4:5]
	s_andn2_b64 vcc, exec, s[44:45]
	s_mov_b64 s[26:27], -1
	s_cbranch_vccnz .LBB0_175
	v_lshlrev_b32_e32 v160, 6, v91
	v_lshl_add_u64 v[92:93], s[18:19], 0, v[160:161]
	s_mov_b64 s[26:27], 0

; #define RAW_BARRIER() do { asm volatile("s_waitcnt lgkmcnt(0)" ::: "memory"); __builtin_amdgcn_s_barrier(); } while (0)
;   DI void operator()(int mt, int nt, int wm, int wn, int r, int h, f32x16 (&acc)[WM][2]) const {
;     ...
;       RAW_BARRIER();
; #pragma unroll
;       for (int mh = 0; mh < 2; ++mh)
; #pragma unroll
;         for (int ni = 0; ni < 2; ++ni)
; #pragma unroll
;           for (int i = 0; i < 16; ++i)
;             T[(wm * 64 + mh * 32 + (i & 3) + 8 * (i >> 2) + 4 * h) * LD + wn * 64 + ni * 32 + r] = acc[ps * 2 + mh][ni][i];
;       RAW_BARRIER();
;       const int ropemode0 = (nt < 4) ? 1 : ((nt >= 14 && nt <= 16) ? 2 : 0);
; #pragma unroll
;       for (int j = 0; j < 8; ++j) {
;         const int id = tid + 256 * j;
;         const int lr = id >> 4, cc = id & 15;
;         const int row = mt * (WM * 64) + (lr >> 6) * (WM * 32) + ps * 64 + (lr & 63);
;         const int col0 = nt * 128 + cc * 8;
;         if (col0 < PW) {
;           const int t = row % NTOK;
;           const int ropemode = (t >= NCTX) ? ropemode0 : 0;
;           const float4 a0 = *(const float4*)(T + lr * LD + cc * 8), a1 = *(const float4*)(T + lr * LD + cc * 8 + 4);
;           const float4 b0 = *(const float4*)(bias + col0), b1 = *(const float4*)(bias + col0 + 4);
;           float v[8] = {a0.x + b0.x, a0.y + b0.y, a0.z + b0.z, a0.w + b0.w, a1.x + b1.x, a1.y + b1.y, a1.z + b1.z, a1.w + b1.w};
.LBB0_281:
	s_waitcnt lgkmcnt(0)
	s_barrier
	ds_write_b32 v133, v0
	ds_write_b32 v133, v4 offset:64
	ds_write_b32 v133, v8 offset:128
	ds_write_b32 v133, v12 offset:192
	ds_write_b32 v133, v1 offset:528
	ds_write_b32 v133, v5 offset:592
	ds_write_b32 v133, v9 offset:656
	ds_write_b32 v133, v13 offset:720
	ds_write_b32 v133, v2 offset:1056
	ds_write_b32 v133, v6 offset:1120
	ds_write_b32 v133, v10 offset:1184
	ds_write_b32 v133, v14 offset:1248
	ds_write_b32 v133, v3 offset:1584
	ds_write_b32 v133, v7 offset:1648
	ds_write_b32 v133, v11 offset:1712
	ds_write_b32 v133, v15 offset:1776
	ds_write_b32 v133, v16 offset:8448
	ds_write_b32 v133, v20 offset:8512
	ds_write_b32 v133, v24 offset:8576
	ds_write_b32 v133, v28 offset:8640
	ds_write_b32 v133, v17 offset:8976
	ds_write_b32 v133, v21 offset:9040
	ds_write_b32 v133, v25 offset:9104
	ds_write_b32 v133, v29 offset:9168
	ds_write_b32 v133, v18 offset:9504
	ds_write_b32 v133, v22 offset:9568
	ds_write_b32 v133, v26 offset:9632
	ds_write_b32 v133, v30 offset:9696
	ds_write_b32 v133, v19 offset:10032
	ds_write_b32 v133, v23 offset:10096
	ds_write_b32 v133, v27 offset:10160
	ds_write_b32 v133, v31 offset:10224
	ds_write_b32 v133, v32 offset:16896
	ds_write_b32 v133, v36 offset:16960
	ds_write_b32 v133, v40 offset:17024
	ds_write_b32 v133, v44 offset:17088
	ds_write_b32 v133, v33 offset:17424
	ds_write_b32 v133, v37 offset:17488
	ds_write_b32 v133, v41 offset:17552
	ds_write_b32 v133, v45 offset:17616
	ds_write_b32 v133, v34 offset:17952
	ds_write_b32 v133, v38 offset:18016
	ds_write_b32 v133, v42 offset:18080
	ds_write_b32 v133, v46 offset:18144
	ds_write_b32 v133, v35 offset:18480
	ds_write_b32 v133, v39 offset:18544
	ds_write_b32 v133, v43 offset:18608
	ds_write_b32 v133, v47 offset:18672
	ds_write_b32 v133, v48 offset:25344
	ds_write_b32 v133, v52 offset:25408
	ds_write_b32 v133, v56 offset:25472
	ds_write_b32 v133, v60 offset:25536
	ds_write_b32 v133, v49 offset:25872
	ds_write_b32 v133, v53 offset:25936
	ds_write_b32 v133, v57 offset:26000
	ds_write_b32 v133, v61 offset:26064
	ds_write_b32 v133, v50 offset:26400
	ds_write_b32 v133, v54 offset:26464
	ds_write_b32 v133, v58 offset:26528
	ds_write_b32 v133, v62 offset:26592
	ds_write_b32 v133, v51 offset:26928
	ds_write_b32 v133, v55 offset:26992
	ds_write_b32 v133, v59 offset:27056
	ds_write_b32 v133, v63 offset:27120
	s_waitcnt lgkmcnt(0)
	s_or_b32 s43, s28, 64
	v_add_u32_e32 v28, s43, v144
	s_barrier
	s_and_saveexec_b64 s[8:9], s[6:7]
	s_cbranch_execz .LBB0_290
	v_or_b32_e32 v24, v28, v110
	v_mul_hi_i32 v16, v24, s55
	ds_read_b128 v[4:7], v111
	ds_read_b128 v[12:15], v111 offset:16
	v_lshrrev_b32_e32 v17, 31, v16
	v_ashrrev_i32_e32 v16, 9, v16
	v_add_u32_e32 v16, v16, v17
	v_mul_i32_i24_e32 v16, 0x900, v16
	v_sub_u32_e32 v25, v24, v16
	s_xor_b64 s[26:27], s[46:47], -1
	v_cmp_lt_i32_e32 vcc, s62, v25
	s_and_b64 s[28:29], vcc, s[26:27]
	s_waitcnt lgkmcnt(0)
	v_pk_add_f32 v[4:5], v[4:5], v[220:221]
	v_pk_add_f32 v[6:7], v[6:7], v[222:223]
	v_pk_add_f32 v[0:1], v[12:13], v[224:225]
	v_pk_add_f32 v[2:3], v[14:15], v[226:227]
	s_and_saveexec_b64 s[26:27], s[28:29]
	s_cbranch_execz .LBB0_288
	s_lshl_b64 s[28:29], s[24:25], 2
	s_add_u32 s28, s14, s28
	v_lshlrev_b32_e32 v12, 2, v132
	s_addc_u32 s29, s15, s29
	global_load_dwordx4 v[8:11], v12, s[28:29] offset:16
	global_load_dwordx4 v[16:19], v12, s[28:29]
	v_add_u32_e32 v12, v102, v12
	ds_read_b128 v[20:23], v12
	ds_read_b128 v[12:15], v12 offset:16
	v_add_u32_e32 v26, 0xffffff00, v25
	v_lshrrev_b32_e32 v26, 6, v26
	v_and_b32_e32 v25, 63, v25
	v_cndmask_b32_e64 v25, v25, v26, s[4:5]
	s_andn2_b64 vcc, exec, s[44:45]
	s_mov_b64 s[28:29], -1
	s_cbranch_vccnz .LBB0_285
	v_lshlrev_b32_e32 v160, 6, v25
	v_lshl_add_u64 v[26:27], s[18:19], 0, v[160:161]
	s_mov_b64 s[28:29], 0
